# stack: sel fast path (raw scores, gap-interleaved exp, 4 sum accumulators) + permlane32_swap row-max in cmp/win/MLA loops + start-up grid.sync removed
# speedup vs baseline: 1.0077x; 1.0077x over previous
; __global__ void __launch_bounds__(NTHREADS) mega_fwd(Args args) {
;     ...
;     cg::grid_group grid = cg::this_grid();
;     const int G = gridDim.x, bx = blockIdx.x;
;     ...
;     unsigned char* ws = args.ws;
;     float* out = args.out;
;     bf16_t* WGU = (bf16_t*)(ws + WS_WGU); bf16_t* WD = (bf16_t*)(ws + WS_WD); bf16_t* WIN = (bf16_t*)(ws + WS_WIN); bf16_t* WVN = (bf16_t*)(ws + WS_WVN);
;     bf16_t* WUQ = (bf16_t*)(ws + WS_WUQ); bf16_t* WKN = (bf16_t*)(ws + WS_WKN); bf16_t* WVM = (bf16_t*)(ws + WS_WVM); bf16_t* W1K = (bf16_t*)(ws + WS_W1K);
;     bf16_t* W1V = (bf16_t*)(ws + WS_W1V); bf16_t* WOUT = (bf16_t*)(ws + WS_WOUT);
;     float* TAB128 = (float*)(ws + WS_TAB128); float* TAB64 = (float*)(ws + WS_TAB64); float* SSQ = (float*)(ws + WS_SSQ); float* CBIAS = (float*)(ws + WS_MISC);
;     float* HCP = (float*)(ws + WS_HCP); bf16_t* KC = (bf16_t*)(ws + WS_KC); bf16_t* VCT = KC + 2 * 1024 * 128;
;     bf16_t* XB = (bf16_t*)(ws + WS_XB); bf16_t* H = (bf16_t*)(ws + WS_H);
;     float* PRE3 = (float*)(ws + 384 * MiB);
;     bf16_t* D0 = (bf16_t*)out; bf16_t* D1 = D0 + (size_t)M * DM;
;     bf16_t* CQ = (bf16_t*)(ws + WS_CQ); bf16_t* CKV = (bf16_t*)(ws + WS_CKV); bf16_t* KR = (bf16_t*)(ws + WS_KR); bf16_t* GL = (bf16_t*)(ws + WS_GL);
;     bf16_t* QN = (bf16_t*)(ws + WS_QN); bf16_t* KCR = (bf16_t*)(ws + WS_KCR); bf16_t* VCR = (bf16_t*)(ws + WS_VCR); bf16_t* KS = (bf16_t*)(ws + WS_KS);
;     bf16_t* KW = (bf16_t*)(ws + WS_KW); bf16_t* VTN = (bf16_t*)(ws + WS_VTN); bf16_t* QM = (bf16_t*)(ws + WS_QM); bf16_t* KN = (bf16_t*)(ws + WS_KN);
;     bf16_t* VT = (bf16_t*)(ws + WS_VT); float* OACC = (float*)(ws + WS_OACC);
;     const int lo = args.ph_lo, hi_ph = args.ph_hi;
;     unsigned* barctr = (unsigned*)(ws + WS_MISC + 65536); unsigned epoch = 0u;
;     grid.sync();
_Z8mega_fwd4Args:
	s_load_dwordx2 s[70:71], s[0:1], 0xe0
	s_load_dword s33, s[0:1], 0xe8
	s_add_u32 s6, s0, 0xe8
	v_and_b32_e32 v1, 0x3fffffff, v0
	s_addc_u32 s7, s1, 0
	v_cmp_eq_u32_e32 vcc, 0, v1
	s_waitcnt lgkmcnt(0)
	s_branch .LBB0_10
	s_barrier
	s_and_saveexec_b64 s[4:5], vcc
	s_cbranch_execz .LBB0_10
	buffer_wbl2 sc1
	s_load_dwordx2 s[6:7], s[6:7], 0x58
	s_mov_b64 s[8:9], exec
	v_mbcnt_lo_u32_b32 v1, s8, 0
	v_mbcnt_hi_u32_b32 v1, s9, v1
	v_cmp_eq_u32_e32 vcc, 0, v1
	s_waitcnt lgkmcnt(0)
	s_load_dword s3, s[6:7], 0x28
	s_and_saveexec_b64 s[10:11], vcc
	s_cbranch_execz .LBB0_3
	s_bcnt1_i32_b64 s8, s[8:9]
	v_mov_b32_e32 v2, 0
	v_mov_b32_e32 v3, s8
	global_atomic_add v2, v2, v3, s[6:7] offset:32 sc0
